# GEMM-up epilogue rewritten by hand: A rows staged as 4*fr+m per lane (64 DPP moves instead of 448), packed f32 conv/silu arithmetic
# speedup vs baseline: 1.0224x; 1.0152x over previous
; #define PG8_STAGE(bufoff, gbase, voff) do { _Pragma("unroll") for (int _i = 0; _i < 2; ++_i) \
;         __builtin_amdgcn_global_load_lds((const unsigned*)((const char*)(gbase) + (voff)[_i]), (LAS unsigned*)(lds + (bufoff) + ldsw + _i * 8192), 16, 0, 0); } while (0)
; #define PG8_WAIT_V(n) asm volatile("s_waitcnt vmcnt(" #n ")" ::: "memory")
; #define PG8_BAR __builtin_amdgcn_s_barrier()
; template <class Epi, class Sched>
; __device__ __forceinline__ void gemm_phase(LAS unsigned char* lds, const Gemm g, const Sched& S, const Epi& E) {
;     const int tid = threadIdx.x, wid = __builtin_amdgcn_readfirstlane(tid >> 6), lane = tid & 63, wr = wid >> 2, wc = wid & 3, fr = lane & 15, fq = lane >> 4;
;     const int K = g.K, nt = K / BK, lda = g.lda;
;     unsigned voffA[2], voffB[2];
; #pragma unroll
;     for (int i = 0; i < 2; ++i) { int R, C; stage_rc(tid * 16 + i * 8192, R, C); const int Rb = Epi::PERM ? ((R & ~31) + perm32(R & 31)) : R;
;         voffA[i] = (unsigned)(R * lda + C) * 2u; voffB[i] = (unsigned)(Rb * K + C) * 2u; }
;     const size_t kstep = (size_t)(BK * 2);
;     const size_t hstepA = (size_t)HALF * lda * 2, hstepB = (size_t)HALF * K * 2;
;     const size_t tstepA = 2 * hstepA, tstepB = 2 * hstepB;
;     const unsigned ldsw = (unsigned)wid * 1024u;
;     const int aoff = lds_byte(wr * 64 + fr, fq * 8), boff = lds_byte(wc * 32 + fr, fq * 8);
;     ...
;     Unit cur, nxt; int ui = 0;
;     if (!S.next(0, cur)) return;
;     f32x4 acc[2][2][4][2];
; #pragma unroll
;     for (int a = 0; a < 2; ++a)
; #pragma unroll
;         for (int b = 0; b < 2; ++b)
; #pragma unroll
;             for (int m = 0; m < 4; ++m)
; #pragma unroll
;                 for (int n = 0; n < 2; ++n) acc[a][b][m][n] = (f32x4){0.f, 0.f, 0.f, 0.f};
;     bf16x8 At[4][2], B0[2][2], B1[2][2];
;     const char* cA = (const char*)g.A + (size_t)cur.pm * tstepA; const char* cB = (const char*)g.Bt + (size_t)cur.pn * tstepB;
;     PG8_STAGE(PG8_SB(0, 0), cB, voffB); PG8_STAGE(PG8_SB(0, 1), cB + hstepB, voffB); PG8_STAGE(PG8_SA(0, 0), cA, voffA); PG8_STAGE(PG8_SA(0, 1), cA + hstepA, voffA);
;     if (wr == 1) PG8_BAR;
;     PG8_WAIT_V(2); PG8_BAR;
;     PG8_STAGE(PG8_SB(1, 0), cB + kstep, voffB); PG8_STAGE(PG8_SA(1, 0), cA + kstep, voffA); PG8_STAGE(PG8_SB(1, 1), cB + hstepB + kstep, voffB);
;     PG8_WAIT_V(6); PG8_BAR;
.LBB0_918:
	s_cmp_lt_i32 s92, 9
	s_cselect_b64 s[0:1], -1, 0
	s_and_b64 s[10:11], s[0:1], s[4:5]
	s_andn2_b64 vcc, exec, s[10:11]
	s_cbranch_vccnz .LBB0_946
	v_readlane_b32 s0, v245, 0
	v_readlane_b32 s1, v245, 1
	s_cmpk_gt_i32 s0, 0xaff
	v_readfirstlane_b32 s1, v209
	s_cbranch_scc1 .LBB0_946
	s_mov_b64 s[12:13], s[88:89]
	s_mov_b64 s[14:15], s[90:91]
	s_add_u32 s3, s14, 0x5300000
	s_mov_b64 s[16:17], s[92:93]
	s_mov_b64 s[18:19], s[94:95]
	s_addc_u32 s56, s15, 0
	s_add_u32 s57, s14, 0x1700000
	v_writelane_b32 v245, s12, 23
	v_lshrrev_b32_e32 v0, 5, v209
	v_lshrrev_b32_e32 v2, 1, v209
	v_writelane_b32 v245, s13, 24
	v_writelane_b32 v245, s14, 25
	v_and_b32_e32 v0, 4, v0
	v_bfe_u32 v1, v209, 2, 2
	v_and_b32_e32 v12, 24, v2
	v_writelane_b32 v245, s15, 26
	v_or3_b32 v0, v0, v1, v12
	v_lshlrev_b32_e32 v1, 4, v209
	v_writelane_b32 v245, s16, 27
	v_add_u32_e32 v8, 0x2000, v1
	v_writelane_b32 v245, s17, 28
	v_lshrrev_b32_e32 v2, 7, v8
	s_movk_i32 s0, 0xe0
	v_and_b32_e32 v4, 32, v209
	v_writelane_b32 v245, s18, 29
	v_and_or_b32 v3, v2, s0, v0
	v_bitop3_b32 v9, v1, v4, 48 bitop3:0x6c
	v_and_b32_e32 v10, 64, v209
	v_bfe_u32 v11, v209, 2, 4
	s_movk_i32 s0, 0xf0
	v_writelane_b32 v245, s19, 30
	v_or_b32_e32 v1, v9, v10
	v_lshrrev_b32_e32 v2, 7, v209
	v_lshl_or_b32 v2, v11, 2, v2
	v_or_b32_e32 v2, 64, v2
	v_lshl_or_b32 v182, v2, 12, v1
	v_lshrrev_b32_e32 v2, 3, v209
	s_movk_i32 s0, 0x60
	v_readlane_b32 s6, v245, 0
	s_addc_u32 s58, s15, 0
	v_and_or_b32 v0, v2, s0, v0
	s_movk_i32 s0, 0x70
	s_ashr_i32 s60, s6, 31
	v_lshl_or_b32 v184, v0, 12, v1
	v_lshrrev_b32_e32 v0, 7, v209
	v_lshl_or_b32 v0, v11, 2, v0
	s_lshr_b32 s0, s60, 29
	s_add_i32 s0, s6, s0
	s_lshr_b32 s4, s1, 6
	s_ashr_i32 s5, s0, 3
	s_and_b32 s0, s0, -8
	s_lshr_b32 s2, s1, 8
	s_lshl_b32 s59, s4, 10
	s_sub_i32 s0, s6, s0
	s_cmp_lt_i32 s0, 0
	s_movk_i32 s61, 0x161
	s_cselect_b32 s6, s61, 0x160
	s_mul_i32 s0, s0, s6
	s_add_i32 s0, s0, s5
	s_mul_hi_i32 s5, s0, 0x2e8ba2e9
	s_lshr_b32 s6, s5, 31
	s_ashr_i32 s5, s5, 5
	s_add_i32 s5, s5, s6
	s_lshl_b32 s6, s5, 2
	s_mulk_i32 s5, 0xb0
	s_sub_i32 s5, s0, s5
	s_sext_i32_i16 s0, s5
	v_readlane_b32 s7, v245, 1
	s_bfe_u32 s0, s0, 0x2001d
	s_add_i32 s7, s5, s0
	s_sext_i32_i16 s0, s7
	s_and_b32 s7, s7, 0xfffc
	s_sub_i32 s5, s5, s7
	s_sext_i32_i16 s5, s5
	s_lshr_b32 s0, s0, 2
	s_add_i32 s52, s6, s5
	s_ashr_i32 s53, s52, 31
	s_bfe_i64 s[8:9], s[0:1], 0x100000
	s_lshl_b64 s[6:7], s[52:53], 20
	s_lshl_b64 s[8:9], s[8:9], 20
	s_add_u32 s8, s57, s8
	s_addc_u32 s9, s58, s9
	s_add_i32 s62, s59, 0
	s_add_i32 m0, s62, 0x10000
	v_lshl_or_b32 v180, v3, 12, v1
	global_load_lds_dwordx4 v184, s[8:9]
	s_add_i32 m0, s62, 0x12000
	s_add_u32 s12, s8, 0x80000
	global_load_lds_dwordx4 v180, s[8:9]
	s_addc_u32 s13, s9, 0
	s_add_i32 m0, s62, 0x14000
	v_lshl_or_b32 v186, v0, 12, v1
	global_load_lds_dwordx4 v184, s[12:13]
	s_add_i32 m0, s62, 0x16000
	s_add_u32 s6, s3, s6
	s_addc_u32 s7, s56, s7
	s_add_i32 s63, s62, 0x2000
	global_load_lds_dwordx4 v180, s[12:13]
	s_mov_b32 m0, s62
	s_add_u32 s12, s6, 0x80000
	global_load_lds_dwordx4 v186, s[6:7]
	s_mov_b32 m0, s63
	s_addc_u32 s13, s7, 0
	s_add_i32 s64, s62, 0x4000
	global_load_lds_dwordx4 v182, s[6:7]
	s_mov_b32 m0, s64
	s_add_i32 s65, s62, 0x6000
	global_load_lds_dwordx4 v186, s[12:13]
	s_mov_b32 m0, s65
	v_mov_b32_e32 v189, 0
	global_load_lds_dwordx4 v182, s[12:13]
	v_mov_b32_e32 v185, v189
	v_mov_b32_e32 v181, v189
	v_mov_b32_e32 v187, v189
	v_mov_b32_e32 v183, v189
	s_cmp_eq_u32 s2, 1
	s_mov_b32 s92, s50
	s_mov_b32 s94, s48
	s_mov_b32 s66, 0
	v_lshl_add_u64 v[6:7], s[8:9], 0, v[184:185]
	v_lshl_add_u64 v[4:5], s[8:9], 0, v[180:181]
	v_lshl_add_u64 v[0:1], s[6:7], 0, v[186:187]
	s_cselect_b64 s[12:13], -1, 0
	s_cmp_lg_u32 s2, 1
	v_lshl_add_u64 v[2:3], s[6:7], 0, v[182:183]
	s_cbranch_scc1 .LBB0_922
	s_barrier
; #define LAS __attribute__((address_space(3)))
; #define PG8_STAGE(bufoff, gbase, voff) do { _Pragma("unroll") for (int _i = 0; _i < 2; ++_i) \
;         __builtin_amdgcn_global_load_lds((const unsigned*)((const char*)(gbase) + (voff)[_i]), (LAS unsigned*)(lds + (bufoff) + ldsw + _i * 8192), 16, 0, 0); } while (0)
; #define PG8_BAR __builtin_amdgcn_s_barrier()
; template <class Epi, class Sched>
; __device__ __forceinline__ void gemm_phase(LAS unsigned char* lds, const Gemm g, const Sched& S, const Epi& E) {
;     ...
;     const char* cA = (const char*)g.A + (size_t)cur.pm * tstepA; const char* cB = (const char*)g.Bt + (size_t)cur.pn * tstepB;
;     PG8_STAGE(PG8_SB(0, 0), cB, voffB); PG8_STAGE(PG8_SB(0, 1), cB + hstepB, voffB); PG8_STAGE(PG8_SA(0, 0), cA, voffA); PG8_STAGE(PG8_SA(0, 1), cA + hstepA, voffA);
;     if (wr == 1) PG8_BAR;
;     PG8_WAIT_V(2); PG8_BAR;
;     PG8_STAGE(PG8_SB(1, 0), cB + kstep, voffB); PG8_STAGE(PG8_SA(1, 0), cA + kstep, voffA); PG8_STAGE(PG8_SB(1, 1), cB + hstepB + kstep, voffB);
;     PG8_WAIT_V(6); PG8_BAR;
;     __device__ __forceinline__ void operator()(const f32x4 (&acc)[2][2][4][2], const pg8::Unit& u, int wr, int wc, int fr, int fq) const {
;         asm volatile("s_nop 7\n\ts_nop 7\n\ts_nop 7" ::: "memory");
;         const int cc0 = wc * 32 + 8 * fq;
;         if (fr >= 14) {
; #pragma unroll
;             for (int ai = 0; ai < 2; ++ai)
; #pragma unroll
;                 for (int bj = 0; bj < 2; ++bj)
; #pragma unroll
;                     for (int n = 0; n < 2; ++n) *(LAS f32x4*)(xb + ((2 * ai + wr) * 2 + (fr - 14)) * 256 + bj * 128 + cc0 + 4 * n) = acc[ai][bj][3][n];
;             if (wr == 1) {
; #pragma unroll
;                 for (int bj = 0; bj < 2; ++bj)
; #pragma unroll
;                     for (int n = 0; n < 2; ++n) *(f32x4*)(halo + ((size_t)u.pm * 2 + (fr - 14)) * UPW + u.pn * 256 + bj * 128 + cc0 + 4 * n) = acc[1][bj][3][n];
;             }
;         }
;         if (wr == 0 && fr < 2) {
; #pragma unroll
;             for (int bj = 0; bj < 2; ++bj)
; #pragma unroll
;                 for (int n = 0; n < 2; ++n) *(f32x4*)(head + ((size_t)u.pm * 2 + fr) * UPW + u.pn * 256 + bj * 128 + cc0 + 4 * n) = acc[0][bj][0][n];
;         }
;         asm volatile("s_waitcnt lgkmcnt(0)" ::: "memory"); __builtin_amdgcn_s_barrier(); asm volatile("" ::: "memory");
;         const int row0 = u.pm * 256 + wr * 64 + fr;
.LBB0_922:
	v_readlane_b32 s24, v245, 23
	v_readlane_b32 s26, v245, 25
	v_readlane_b32 s27, v245, 26
	s_add_u32 s14, s26, 0x9300000
	s_addc_u32 s15, s27, 0
	s_add_u32 s16, s26, 0x4d80000
	s_addc_u32 s17, s27, 0
	s_add_u32 s18, s26, 0x4800000
	s_addc_u32 s19, s27, 0
	s_lshl_b32 s4, s4, 5
	s_mov_b64 s[20:21], 0x80
	s_and_b32 s26, s4, 0x60
	s_add_i32 m0, s62, 0x18000
	v_lshl_add_u64 v[6:7], v[6:7], 0, s[20:21]
	s_sext_i32_i16 s76, s0
	s_lshl_b32 s0, s2, 13
	s_lshl_b32 s22, s26, 7
	s_waitcnt vmcnt(2)
	s_barrier
	global_load_lds_dwordx4 v[6:7], off
	v_lshl_add_u64 v[4:5], v[4:5], 0, s[20:21]
	s_add_i32 m0, s62, 0x1a000
	s_add_i32 s67, s62, 0x8000
	s_add_i32 s68, s62, 0xa000
	global_load_lds_dwordx4 v[4:5], off
	v_lshl_add_u64 v[0:1], v[0:1], 0, s[20:21]
	s_mov_b32 m0, s67
	s_add_u32 s4, s8, 0x80080
	global_load_lds_dwordx4 v[0:1], off
	v_lshl_add_u64 v[0:1], v[2:3], 0, s[20:21]
	s_mov_b32 m0, s68
	s_addc_u32 s5, s9, 0
	global_load_lds_dwordx4 v[0:1], off
	s_add_i32 m0, s62, 0x1c000
	v_lshl_add_u64 v[0:1], s[4:5], 0, v[184:185]
	global_load_lds_dwordx4 v[0:1], off
	v_lshl_add_u64 v[0:1], s[4:5], 0, v[180:181]
	s_add_i32 m0, s62, 0x1e000
	v_and_b32_e32 v190, 15, v209
	global_load_lds_dwordx4 v[0:1], off
	v_lshlrev_b32_e32 v0, 1, v12
	v_lshlrev_b32_e32 v2, 2, v209
	v_lshl_or_b32 v1, v190, 6, v0
	v_and_b32_e32 v2, 32, v2
	v_bitop3_b32 v1, v1, s0, v2 bitop3:0xde
	v_lshlrev_b32_e32 v3, 6, v209
	s_movk_i32 s0, 0x3c0
	v_and_or_b32 v0, v3, s0, v0
	s_cmpk_lt_u32 s1, 0x100
	v_readlane_b32 s25, v245, 24
	v_bitop3_b32 v212, s22, v0, v2 bitop3:0xf6
	s_cselect_b64 s[22:23], -1, 0
	s_cmpk_gt_u32 s1, 0xff
	v_cmp_gt_u32_e32 vcc, 2, v190
	v_readlane_b32 s28, v245, 27
	v_readlane_b32 s29, v245, 28
	v_readlane_b32 s30, v245, 29
	s_cselect_b64 s[24:25], -1, 0
	v_or_b32_e32 v192, s26, v12
	s_and_b64 s[26:27], s[22:23], vcc
	v_readlane_b32 s36, v245, 5
	v_lshl_or_b32 v193, s2, 6, v190
	s_lshl_b32 s2, s2, 11
	s_xor_b64 s[28:29], s[26:27], -1
	s_ashr_i32 s69, s30, 31
	s_add_i32 s4, 0, 0x20000
	s_add_i32 s5, 0, 0x21000
	v_readlane_b32 s44, v245, 13
	v_readlane_b32 s31, v245, 30
	s_mov_b32 s70, s30
	v_readlane_b32 s45, v245, 14
	s_add_u32 s30, s44, 0xb000
	s_addc_u32 s31, s45, 0
	s_add_u32 s34, s44, 0x16000
	s_addc_u32 s35, s45, 0
	v_readlane_b32 s37, v245, 6
	s_add_u32 s36, s44, 0x5800
	v_readlane_b32 s38, v245, 7
	s_addc_u32 s37, s45, 0
	v_readlane_b32 s39, v245, 8
	s_add_u32 s38, s44, 0x10800
	v_readlane_b32 s40, v245, 9
	s_addc_u32 s39, s45, 0
	v_readlane_b32 s41, v245, 10
	s_add_u32 s40, s44, 0x1b800
	v_readlane_b32 s42, v245, 11
	v_readlane_b32 s46, v245, 15
	s_addc_u32 s41, s45, 0
	v_lshl_add_u32 v0, v190, 10, s2
	v_readlane_b32 s43, v245, 12
	v_readlane_b32 s47, v245, 16
	s_add_u32 s42, s46, 0x5800
	v_add_u32_e32 v0, 0xffffc800, v0
	v_lshlrev_b32_e32 v2, 2, v192
	s_addc_u32 s43, s47, 0
	s_add_i32 s2, s4, s2
	v_add3_u32 v213, s4, v0, v2
	v_add3_u32 v214, s5, v0, v2
	s_add_i32 s4, s2, 0xfffff800
	v_lshlrev_b32_e32 v0, 10, v209
	v_add_u32_e32 v215, s4, v2
	v_and_b32_e32 v0, 0x400, v0
	v_add_u32_e32 v217, s2, v2
	v_add_u32_e32 v216, v215, v0
	v_add_u32_e32 v218, v217, v0
	v_lshlrev_b32_e32 v0, 5, v209
	v_and_b32_e32 v0, 0x3000, v0
	v_lshlrev_b32_e32 v2, 14, v11
	v_or3_b32 v0, v9, v0, v2
	v_add_u32_e32 v196, v0, v10
	v_lshlrev_b32_e32 v0, 5, v209
	s_waitcnt vmcnt(6)
	v_and_b32_e32 v0, 0x3000, v0
	v_or_b32_e32 v0, 0x40000, v0
	v_or3_b32 v0, v9, v0, v2
	s_add_i32 s71, 0, 0x10000
	s_add_i32 s73, 0, 0x14000
	v_cmp_lt_u32_e64 s[0:1], 13, v190
	v_add_u32_e32 v194, -14, v190
	v_mov_b32_e32 v195, v189
	v_add_u32_e32 v219, 0xfffff810, v218
	v_add_u32_e32 v220, 0xfffffe10, v217
	v_add_u32_e32 v221, 0xfffffc10, v217
	v_mov_b32_e32 v197, v189
	v_add_u32_e32 v198, v0, v10
	v_mov_b32_e32 v199, v189
	v_mov_b64_e32 v[200:201], 0xb00
	v_mov_b64_e32 v[202:203], 0xaff
	v_add_u32_e32 v222, s71, v212
	v_add_u32_e32 v223, s73, v212
	v_add_u32_e32 v224, 0, v1
	s_mov_b32 s74, 0xb000
	s_movk_i32 s75, 0x2c00
	v_lshlrev_b32_e32 v188, 1, v192
	v_mov_b32_e32 v225, 0xb000
	s_barrier
	v_readlane_b32 s48, v245, 17
	v_readlane_b32 s49, v245, 18
	v_readlane_b32 s50, v245, 19
	v_readlane_b32 s51, v245, 20
	s_branch .LBB0_925

; #define LAS __attribute__((address_space(3)))
;     __device__ __forceinline__ void operator()(const f32x4 (&acc)[2][2][4][2], const pg8::Unit& u, int wr, int wc, int fr, int fq) const {
;         asm volatile("s_nop 7\n\ts_nop 7\n\ts_nop 7" ::: "memory");
;         const int cc0 = wc * 32 + 8 * fq;
;         if (fr >= 14) {
; #pragma unroll
;             for (int ai = 0; ai < 2; ++ai)
; #pragma unroll
;                 for (int bj = 0; bj < 2; ++bj)
; #pragma unroll
;                     for (int n = 0; n < 2; ++n) *(LAS f32x4*)(xb + ((2 * ai + wr) * 2 + (fr - 14)) * 256 + bj * 128 + cc0 + 4 * n) = acc[ai][bj][3][n];
;             if (wr == 1) {
; #pragma unroll
;                 for (int bj = 0; bj < 2; ++bj)
; #pragma unroll
;                     for (int n = 0; n < 2; ++n) *(f32x4*)(halo + ((size_t)u.pm * 2 + (fr - 14)) * UPW + u.pn * 256 + bj * 128 + cc0 + 4 * n) = acc[1][bj][3][n];
;             }
;         }
;         if (wr == 0 && fr < 2) {
; #pragma unroll
;             for (int bj = 0; bj < 2; ++bj)
; #pragma unroll
;                 for (int n = 0; n < 2; ++n) *(f32x4*)(head + ((size_t)u.pm * 2 + fr) * UPW + u.pn * 256 + bj * 128 + cc0 + 4 * n) = acc[0][bj][0][n];
;         }
;         asm volatile("s_waitcnt lgkmcnt(0)" ::: "memory"); __builtin_amdgcn_s_barrier(); asm volatile("" ::: "memory");
;         const int row0 = u.pm * 256 + wr * 64 + fr;
;         u32x2 lo[2][4];
; #pragma unroll
;         for (int n = 0; n < 2; ++n) {
;             const int jg = u.pn * 128 + cc0 + 4 * n;
;             const f32x4 g0w = *(const f32x4*)(cw + jg), g1w = *(const f32x4*)(cw + UPW + jg), g2w = *(const f32x4*)(cw + 2 * UPW + jg), gb = *(const f32x4*)(cb + jg);
;             const f32x4 u0w = *(const f32x4*)(cw + DFF + jg), u1w = *(const f32x4*)(cw + UPW + DFF + jg), u2w = *(const f32x4*)(cw + 2 * UPW + DFF + jg), ub = *(const f32x4*)(cb + DFF + jg);
.LBB0_931:
	s_nop 7
	s_nop 7
	s_nop 7
	v_cndmask_b32_e64 v112, 0, 1, s[12:13]
	v_cmp_ne_u32_e64 s[6:7], 1, v112
	v_cmp_eq_u32_e64 s[80:81], 15, v190
	s_and_saveexec_b64 s[8:9], s[80:81]
	s_cbranch_execz .Lupc2_a
	v_add_u32_e32 v112, 0xfffffc00, v213
	ds_write_b128 v112, v[108:111]
	ds_write_b128 v112, v[104:107] offset:1024
	ds_write_b128 v112, v[44:47] offset:16
	ds_write_b128 v112, v[40:43] offset:1040
	ds_write_b128 v112, v[100:103] offset:512
	ds_write_b128 v112, v[96:99] offset:1536
	ds_write_b128 v112, v[36:39] offset:528
	ds_write_b128 v112, v[32:35] offset:1552
	ds_write_b128 v112, v[76:79] offset:4096
	ds_write_b128 v112, v[72:75] offset:5120
	ds_write_b128 v112, v[12:15] offset:4112
	ds_write_b128 v112, v[8:11] offset:5136
	ds_write_b128 v112, v[68:71] offset:4608
	ds_write_b128 v112, v[64:67] offset:5632
	ds_write_b128 v112, v[4:7] offset:4624
	ds_write_b128 v112, v[0:3] offset:5648
	s_and_b64 vcc, exec, s[6:7]
	s_cbranch_vccnz .Lupc2_a
	s_ashr_i32 s53, s52, 31
	v_lshl_add_u64 v[112:113], s[52:53], 1, v[194:195]
	v_mov_b64_e32 v[126:127], s[18:19]
	s_lshl_b32 s54, s76, 8
	v_mad_u64_u32 v[126:127], s[78:79], v112, s74, v[126:127]
	s_ashr_i32 s55, s54, 31
	v_mad_i32_i24 v127, v113, s74, v127
	v_lshl_add_u64 v[112:113], s[54:55], 2, v[126:127]
	v_lshlrev_b32_e32 v126, 2, v192
	v_mov_b32_e32 v127, v189
	v_lshl_add_u64 v[112:113], v[112:113], 0, v[126:127]
	s_mov_b32 s82, 0xffff5000
	s_mov_b32 s83, -1
	v_lshl_add_u64 v[126:127], v[112:113], 0, s[82:83]
	global_store_dwordx4 v[126:127], v[76:79], off
	global_store_dwordx4 v[112:113], v[72:75], off
	global_store_dwordx4 v[126:127], v[12:15], off offset:16
	global_store_dwordx4 v[112:113], v[8:11], off offset:16
	global_store_dwordx4 v[126:127], v[68:71], off offset:512
	global_store_dwordx4 v[112:113], v[64:67], off offset:512
	global_store_dwordx4 v[126:127], v[4:7], off offset:528
	global_store_dwordx4 v[112:113], v[0:3], off offset:528
.Lupc2_a:
	s_or_b64 exec, exec, s[8:9]
	v_cmp_eq_u32_e64 s[80:81], 0, v190
	s_and_b64 s[80:81], s[80:81], s[22:23]
	s_and_saveexec_b64 s[8:9], s[80:81]
	s_cbranch_execz .Lupc2_b
	v_lshl_or_b32 v126, s52, 1, v190
	v_mov_b64_e32 v[112:113], s[16:17]
	s_ashr_i32 s2, s52, 31
	s_lshl_b32 s54, s76, 8
	v_mad_u64_u32 v[112:113], s[78:79], v126, s74, v[112:113]
	s_ashr_i32 s55, s54, 31
	v_mad_i32_i24 v113, s2, v225, v113
	v_lshl_add_u64 v[112:113], s[54:55], 2, v[112:113]
	v_lshlrev_b32_e32 v126, 2, v192
	v_mov_b32_e32 v127, v189
	v_lshl_add_u64 v[112:113], v[112:113], 0, v[126:127]
	s_mov_b32 s82, 0xb000
	s_mov_b32 s83, 0
	v_lshl_add_u64 v[126:127], v[112:113], 0, s[82:83]
	global_store_dwordx4 v[112:113], v[160:163], off
	global_store_dwordx4 v[126:127], v[122:125], off
	global_store_dwordx4 v[112:113], v[60:63], off offset:16
	global_store_dwordx4 v[126:127], v[52:55], off offset:16
	global_store_dwordx4 v[112:113], v[114:117], off offset:512
	global_store_dwordx4 v[126:127], v[118:121], off offset:512
	global_store_dwordx4 v[112:113], v[56:59], off offset:528
	global_store_dwordx4 v[126:127], v[48:51], off offset:528
.Lupc2_b:
	s_or_b64 exec, exec, s[8:9]
	s_lshl_b32 s54, s76, 7
	v_or_b32_e32 v244, s54, v192
	v_lshlrev_b32_e32 v244, 2, v244
	v_readlane_b32 s84, v245, 13
	v_readlane_b32 s85, v245, 14
	v_readlane_b32 s86, v245, 15
	v_readlane_b32 s87, v245, 16
	s_waitcnt lgkmcnt(0)
	s_barrier
	s_lshl_b32 s2, s52, 8
	v_mad_u32_u24 v243, v190, 3, v193
	v_add_u32_e32 v243, s2, v243
	v_mul_u32_u24_e32 v243, 0x2c00, v243
	s_lshl_b32 s2, s54, 1
	v_add3_u32 v243, v243, s2, v188
	v_mov_b32_e32 v126, 0xbfb8aa3b
	v_mov_b32_e32 v127, 0xbfb8aa3b
	v_cmp_ne_u32_e64 s[78:79], 0, v190
	s_nop 3
	s_or_b64 s[78:79], s[78:79], s[24:25]
	global_load_dwordx4 v[144:147], v244, s[84:85]
	global_load_dwordx4 v[152:155], v244, s[30:31]
	global_load_dwordx4 v[148:151], v244, s[34:35]
	global_load_dwordx4 v[156:159], v244, s[86:87]
	global_load_dwordx4 v[136:139], v244, s[36:37]
	global_load_dwordx4 v[128:131], v244, s[38:39]
	global_load_dwordx4 v[132:135], v244, s[40:41]
	global_load_dwordx4 v[140:143], v244, s[42:43]
	v_mov_b32_e32 v172, 0
	v_mov_b32_e32 v173, 0
	v_mov_b32_e32 v174, 0
	v_mov_b32_e32 v175, 0
	v_mov_b32_e32 v164, 0
	v_mov_b32_e32 v165, 0
	v_mov_b32_e32 v166, 0
	v_mov_b32_e32 v167, 0
	v_mov_b32_e32 v176, 0
	v_mov_b32_e32 v177, 0
	v_mov_b32_e32 v178, 0
	v_mov_b32_e32 v179, 0
	v_mov_b32_e32 v168, 0
	v_mov_b32_e32 v169, 0
	v_mov_b32_e32 v170, 0
	v_mov_b32_e32 v171, 0
	s_andn2_b64 vcc, exec, s[24:25]
	s_cbranch_vccnz .Lupc2_nocarry00
	ds_read_b128 v[172:175], v215 offset:1024
	ds_read_b128 v[164:167], v215 offset:1536
	ds_read_b128 v[176:179], v215
	ds_read_b128 v[168:171], v215 offset:512
; __device__ __forceinline__ unsigned cvt_pk_bf16(float lo, float hi) { unsigned r; asm volatile("v_cvt_pk_bf16_f32 %0, %1, %2" : "=v"(r) : "v"(lo), "v"(hi)); return r; }
; __device__ __forceinline__ float fast_silu(float x) { return x * fast_sigmoid(x); }
; __device__ __forceinline__ float dpp_shr1(float old, float src) { return __int_as_float(__builtin_amdgcn_update_dpp(__float_as_int(old), __float_as_int(src), 0x111, 0xf, 0xf, false)); }
; __device__ __forceinline__ float dpp_shr2(float old, float src) { return __int_as_float(__builtin_amdgcn_update_dpp(__float_as_int(old), __float_as_int(src), 0x112, 0xf, 0xf, false)); }
; __device__ __forceinline__ float dpp_ror1(float src) { return __int_as_float(__builtin_amdgcn_mov_dpp(__float_as_int(src), 0x121, 0xf, 0xf, true)); }
;     __device__ __forceinline__ void operator()(const f32x4 (&acc)[2][2][4][2], const pg8::Unit& u, int wr, int wc, int fr, int fq) const {
;     ...
; #pragma unroll
;                 for (int m = 0; m < 4; ++m) {
;                     float a[4];
; #pragma unroll
;                     for (int e = 0; e < 4; ++e) {
;                         const float gc = acc[ai][0][m][n][e], uc = acc[ai][1][m][n][e];
;                         float og1, og2, ou1, ou2;
;                         if (m == 0) { og1 = pg1[e]; og2 = pg2[e]; ou1 = pu1[e]; ou2 = pu2[e]; }
;                         else { const float gp = acc[ai][0][m - 1][n][e], up = acc[ai][1][m - 1][n][e]; og1 = dpp_ror1(gp); og2 = dpp_ror2(gp); ou1 = dpp_ror1(up); ou2 = dpp_ror2(up); }
;                         const float gm1 = dpp_shr1(og1, gc), gm2 = dpp_shr2(og2, gc), um1 = dpp_shr1(ou1, uc), um2 = dpp_shr2(ou2, uc);
;                         const float yg = g0w[e] * gm2 + g1w[e] * gm1 + g2w[e] * gc + gb[e];
;                         const float yu = u0w[e] * um2 + u1w[e] * um1 + u2w[e] * uc + ub[e];
;                         a[e] = fast_silu(yg) * yu;
;                     }
;                     u32x2 pk; pk.x = cvt_pk_bf16(a[0], a[1]); pk.y = cvt_pk_bf16(a[2], a[3]);
;                     if (n == 0) lo[ai][m] = pk;
;                     else {
;                         const bool skip = (gi == 0) && (m == 0) && (fr < 2);
;                         if (!skip) __builtin_nontemporal_store((u32x4){lo[ai][m].x, lo[ai][m].y, pk.x, pk.y}, (u32x4*)(ACT + (size_t)(row0 + ai * 128 + m * 16) * DFF + u.pn * 128 + cc0));
;                     }
.Lupc2_nocarry00:
	s_waitcnt vmcnt(0) lgkmcnt(0)
	v_mov_b32_dpp v172, v104 row_shr:1 row_mask:0xf bank_mask:0xf
	v_mov_b32_dpp v176, v108 row_shr:1 row_mask:0xf bank_mask:0xf
	v_mov_b32_dpp v164, v96 row_shr:1 row_mask:0xf bank_mask:0xf
	v_mov_b32_dpp v168, v100 row_shr:1 row_mask:0xf bank_mask:0xf
	v_mov_b32_dpp v173, v105 row_shr:1 row_mask:0xf bank_mask:0xf
	v_mov_b32_dpp v177, v109 row_shr:1 row_mask:0xf bank_mask:0xf
	v_mov_b32_dpp v165, v97 row_shr:1 row_mask:0xf bank_mask:0xf
	v_mov_b32_dpp v169, v101 row_shr:1 row_mask:0xf bank_mask:0xf
	v_mov_b32_dpp v174, v106 row_shr:1 row_mask:0xf bank_mask:0xf
	v_mov_b32_dpp v178, v110 row_shr:1 row_mask:0xf bank_mask:0xf
	v_mov_b32_dpp v166, v98 row_shr:1 row_mask:0xf bank_mask:0xf
	v_mov_b32_dpp v170, v102 row_shr:1 row_mask:0xf bank_mask:0xf
	v_mov_b32_dpp v175, v107 row_shr:1 row_mask:0xf bank_mask:0xf
	v_mov_b32_dpp v179, v111 row_shr:1 row_mask:0xf bank_mask:0xf
	v_mov_b32_dpp v167, v99 row_shr:1 row_mask:0xf bank_mask:0xf
	v_mov_b32_dpp v171, v103 row_shr:1 row_mask:0xf bank_mask:0xf
	v_pk_fma_f32 v[204:205], v[148:149], v[104:105], v[156:157]
	v_pk_fma_f32 v[112:113], v[132:133], v[96:97], v[140:141]
	v_pk_fma_f32 v[206:207], v[150:151], v[106:107], v[158:159]
	v_pk_fma_f32 v[210:211], v[134:135], v[98:99], v[142:143]
	v_pk_fma_f32 v[204:205], v[152:153], v[108:109], v[204:205]
	v_pk_fma_f32 v[112:113], v[128:129], v[100:101], v[112:113]
	v_pk_fma_f32 v[206:207], v[154:155], v[110:111], v[206:207]
	v_pk_fma_f32 v[210:211], v[130:131], v[102:103], v[210:211]
	v_pk_fma_f32 v[204:205], v[144:145], v[122:123], v[204:205]
	v_pk_fma_f32 v[112:113], v[136:137], v[118:119], v[112:113]
	v_pk_fma_f32 v[206:207], v[146:147], v[124:125], v[206:207]
	v_pk_fma_f32 v[210:211], v[138:139], v[120:121], v[210:211]
	v_pk_mul_f32 v[226:227], v[204:205], v[126:127]
	v_pk_mul_f32 v[228:229], v[206:207], v[126:127]
	v_exp_f32_e32 v226, v226
	v_exp_f32_e32 v227, v227
	v_exp_f32_e32 v228, v228
	v_exp_f32_e32 v229, v229
	s_nop 0
	v_pk_add_f32 v[226:227], v[226:227], 1.0 op_sel_hi:[1,0]
	v_pk_add_f32 v[228:229], v[228:229], 1.0 op_sel_hi:[1,0]
	v_rcp_f32_e32 v226, v226
	v_rcp_f32_e32 v227, v227
	v_rcp_f32_e32 v228, v228
	v_rcp_f32_e32 v229, v229
	s_nop 0
	v_pk_mul_f32 v[204:205], v[204:205], v[226:227]
	v_pk_mul_f32 v[206:207], v[206:207], v[228:229]
	v_pk_mul_f32 v[204:205], v[204:205], v[112:113]
	v_pk_mul_f32 v[206:207], v[206:207], v[210:211]
	v_cvt_pk_bf16_f32 v104, v204, v205
	v_cvt_pk_bf16_f32 v105, v206, v207
	v_pk_fma_f32 v[204:205], v[148:149], v[108:109], v[156:157]
	v_pk_fma_f32 v[112:113], v[132:133], v[100:101], v[140:141]
	v_pk_fma_f32 v[206:207], v[150:151], v[110:111], v[158:159]
	v_pk_fma_f32 v[210:211], v[134:135], v[102:103], v[142:143]
	v_pk_fma_f32 v[204:205], v[152:153], v[122:123], v[204:205]
	v_pk_fma_f32 v[112:113], v[128:129], v[118:119], v[112:113]
	v_pk_fma_f32 v[206:207], v[154:155], v[124:125], v[206:207]
	v_pk_fma_f32 v[210:211], v[130:131], v[120:121], v[210:211]
	v_pk_fma_f32 v[204:205], v[144:145], v[160:161], v[204:205]
	v_pk_fma_f32 v[112:113], v[136:137], v[114:115], v[112:113]
	v_pk_fma_f32 v[206:207], v[146:147], v[162:163], v[206:207]
	v_pk_fma_f32 v[210:211], v[138:139], v[116:117], v[210:211]
	v_pk_mul_f32 v[226:227], v[204:205], v[126:127]
	v_pk_mul_f32 v[228:229], v[206:207], v[126:127]
	v_exp_f32_e32 v226, v226
	v_exp_f32_e32 v227, v227
	v_exp_f32_e32 v228, v228
	v_exp_f32_e32 v229, v229
	s_nop 0
	v_pk_add_f32 v[226:227], v[226:227], 1.0 op_sel_hi:[1,0]
	v_pk_add_f32 v[228:229], v[228:229], 1.0 op_sel_hi:[1,0]
	v_rcp_f32_e32 v226, v226
	v_rcp_f32_e32 v227, v227
	v_rcp_f32_e32 v228, v228
	v_rcp_f32_e32 v229, v229
	s_nop 0
	v_pk_mul_f32 v[204:205], v[204:205], v[226:227]
	v_pk_mul_f32 v[206:207], v[206:207], v[228:229]
	v_pk_mul_f32 v[204:205], v[204:205], v[112:113]
	v_pk_mul_f32 v[206:207], v[206:207], v[210:211]
	v_cvt_pk_bf16_f32 v108, v204, v205
	v_cvt_pk_bf16_f32 v109, v206, v207
	v_pk_fma_f32 v[204:205], v[148:149], v[122:123], v[156:157]
	v_pk_fma_f32 v[112:113], v[132:133], v[118:119], v[140:141]
	v_pk_fma_f32 v[206:207], v[150:151], v[124:125], v[158:159]
	v_pk_fma_f32 v[210:211], v[134:135], v[120:121], v[142:143]
	v_pk_fma_f32 v[204:205], v[152:153], v[160:161], v[204:205]
	v_pk_fma_f32 v[112:113], v[128:129], v[114:115], v[112:113]
	v_pk_fma_f32 v[206:207], v[154:155], v[162:163], v[206:207]
	v_pk_fma_f32 v[210:211], v[130:131], v[116:117], v[210:211]
	v_pk_fma_f32 v[204:205], v[144:145], v[172:173], v[204:205]
	v_pk_fma_f32 v[112:113], v[136:137], v[164:165], v[112:113]
	v_pk_fma_f32 v[206:207], v[146:147], v[174:175], v[206:207]
	v_pk_fma_f32 v[210:211], v[138:139], v[166:167], v[210:211]
	v_pk_mul_f32 v[226:227], v[204:205], v[126:127]
	v_pk_mul_f32 v[228:229], v[206:207], v[126:127]
	v_exp_f32_e32 v226, v226
	v_exp_f32_e32 v227, v227
	v_exp_f32_e32 v228, v228
	v_exp_f32_e32 v229, v229
	s_nop 0
	v_pk_add_f32 v[226:227], v[226:227], 1.0 op_sel_hi:[1,0]
	v_pk_add_f32 v[228:229], v[228:229], 1.0 op_sel_hi:[1,0]
	v_rcp_f32_e32 v226, v226
	v_rcp_f32_e32 v227, v227
	v_rcp_f32_e32 v228, v228
	v_rcp_f32_e32 v229, v229
	s_nop 0
	v_pk_mul_f32 v[204:205], v[204:205], v[226:227]
	v_pk_mul_f32 v[206:207], v[206:207], v[228:229]
	v_pk_mul_f32 v[204:205], v[204:205], v[112:113]
	v_pk_mul_f32 v[206:207], v[206:207], v[210:211]
	v_cvt_pk_bf16_f32 v122, v204, v205
	v_cvt_pk_bf16_f32 v123, v206, v207
	v_pk_fma_f32 v[204:205], v[148:149], v[160:161], v[156:157]
	v_pk_fma_f32 v[112:113], v[132:133], v[114:115], v[140:141]
	v_pk_fma_f32 v[206:207], v[150:151], v[162:163], v[158:159]
	v_pk_fma_f32 v[210:211], v[134:135], v[116:117], v[142:143]
	v_pk_fma_f32 v[204:205], v[152:153], v[172:173], v[204:205]
	v_pk_fma_f32 v[112:113], v[128:129], v[164:165], v[112:113]
	v_pk_fma_f32 v[206:207], v[154:155], v[174:175], v[206:207]
	v_pk_fma_f32 v[210:211], v[130:131], v[166:167], v[210:211]
	v_pk_fma_f32 v[204:205], v[144:145], v[176:177], v[204:205]
	v_pk_fma_f32 v[112:113], v[136:137], v[168:169], v[112:113]
	v_pk_fma_f32 v[206:207], v[146:147], v[178:179], v[206:207]
	v_pk_fma_f32 v[210:211], v[138:139], v[170:171], v[210:211]
	v_pk_mul_f32 v[226:227], v[204:205], v[126:127]
	v_pk_mul_f32 v[228:229], v[206:207], v[126:127]
	v_exp_f32_e32 v226, v226
	v_exp_f32_e32 v227, v227
	v_exp_f32_e32 v228, v228
	v_exp_f32_e32 v229, v229
	s_nop 0
	v_pk_add_f32 v[226:227], v[226:227], 1.0 op_sel_hi:[1,0]
	v_pk_add_f32 v[228:229], v[228:229], 1.0 op_sel_hi:[1,0]
	v_rcp_f32_e32 v226, v226
	v_rcp_f32_e32 v227, v227
	v_rcp_f32_e32 v228, v228
	v_rcp_f32_e32 v229, v229
	s_nop 0
	v_pk_mul_f32 v[204:205], v[204:205], v[226:227]
	v_pk_mul_f32 v[206:207], v[206:207], v[228:229]
	v_pk_mul_f32 v[204:205], v[204:205], v[112:113]
	v_pk_mul_f32 v[206:207], v[206:207], v[210:211]
	v_cvt_pk_bf16_f32 v160, v204, v205
	v_cvt_pk_bf16_f32 v161, v206, v207
	ds_read_b128 v[172:175], v215 offset:5120
	ds_read_b128 v[164:167], v215 offset:5632
	ds_read_b128 v[176:179], v215 offset:4096
	ds_read_b128 v[168:171], v215 offset:4608
	s_waitcnt lgkmcnt(0)
; __device__ __forceinline__ unsigned cvt_pk_bf16(float lo, float hi) { unsigned r; asm volatile("v_cvt_pk_bf16_f32 %0, %1, %2" : "=v"(r) : "v"(lo), "v"(hi)); return r; }
; __device__ __forceinline__ float fast_silu(float x) { return x * fast_sigmoid(x); }
; __device__ __forceinline__ float dpp_shr1(float old, float src) { return __int_as_float(__builtin_amdgcn_update_dpp(__float_as_int(old), __float_as_int(src), 0x111, 0xf, 0xf, false)); }
; __device__ __forceinline__ float dpp_shr2(float old, float src) { return __int_as_float(__builtin_amdgcn_update_dpp(__float_as_int(old), __float_as_int(src), 0x112, 0xf, 0xf, false)); }
; __device__ __forceinline__ float dpp_ror1(float src) { return __int_as_float(__builtin_amdgcn_mov_dpp(__float_as_int(src), 0x121, 0xf, 0xf, true)); }
;     __device__ __forceinline__ void operator()(const f32x4 (&acc)[2][2][4][2], const pg8::Unit& u, int wr, int wc, int fr, int fq) const {
;     ...
; #pragma unroll
;                 for (int m = 0; m < 4; ++m) {
;                     float a[4];
; #pragma unroll
;                     for (int e = 0; e < 4; ++e) {
;                         const float gc = acc[ai][0][m][n][e], uc = acc[ai][1][m][n][e];
;                         float og1, og2, ou1, ou2;
;                         if (m == 0) { og1 = pg1[e]; og2 = pg2[e]; ou1 = pu1[e]; ou2 = pu2[e]; }
;                         else { const float gp = acc[ai][0][m - 1][n][e], up = acc[ai][1][m - 1][n][e]; og1 = dpp_ror1(gp); og2 = dpp_ror2(gp); ou1 = dpp_ror1(up); ou2 = dpp_ror2(up); }
;                         const float gm1 = dpp_shr1(og1, gc), gm2 = dpp_shr2(og2, gc), um1 = dpp_shr1(ou1, uc), um2 = dpp_shr2(ou2, uc);
;                         const float yg = g0w[e] * gm2 + g1w[e] * gm1 + g2w[e] * gc + gb[e];
;                         const float yu = u0w[e] * um2 + u1w[e] * um1 + u2w[e] * uc + ub[e];
;                         a[e] = fast_silu(yg) * yu;
;                     }
;                     u32x2 pk; pk.x = cvt_pk_bf16(a[0], a[1]); pk.y = cvt_pk_bf16(a[2], a[3]);
;                     if (n == 0) lo[ai][m] = pk;
;                     else {
;                         const bool skip = (gi == 0) && (m == 0) && (fr < 2);
;                         if (!skip) __builtin_nontemporal_store((u32x4){lo[ai][m].x, lo[ai][m].y, pk.x, pk.y}, (u32x4*)(ACT + (size_t)(row0 + ai * 128 + m * 16) * DFF + u.pn * 128 + cc0));
;                     }
	v_mov_b32_dpp v172, v72 row_shr:1 row_mask:0xf bank_mask:0xf
	v_mov_b32_dpp v176, v76 row_shr:1 row_mask:0xf bank_mask:0xf
	v_mov_b32_dpp v164, v64 row_shr:1 row_mask:0xf bank_mask:0xf
	v_mov_b32_dpp v168, v68 row_shr:1 row_mask:0xf bank_mask:0xf
	v_mov_b32_dpp v173, v73 row_shr:1 row_mask:0xf bank_mask:0xf
	v_mov_b32_dpp v177, v77 row_shr:1 row_mask:0xf bank_mask:0xf
	v_mov_b32_dpp v165, v65 row_shr:1 row_mask:0xf bank_mask:0xf
	v_mov_b32_dpp v169, v69 row_shr:1 row_mask:0xf bank_mask:0xf
	v_mov_b32_dpp v174, v74 row_shr:1 row_mask:0xf bank_mask:0xf
	v_mov_b32_dpp v178, v78 row_shr:1 row_mask:0xf bank_mask:0xf
	v_mov_b32_dpp v166, v66 row_shr:1 row_mask:0xf bank_mask:0xf
	v_mov_b32_dpp v170, v70 row_shr:1 row_mask:0xf bank_mask:0xf
	v_mov_b32_dpp v175, v75 row_shr:1 row_mask:0xf bank_mask:0xf
	v_mov_b32_dpp v179, v79 row_shr:1 row_mask:0xf bank_mask:0xf
	v_mov_b32_dpp v167, v67 row_shr:1 row_mask:0xf bank_mask:0xf
	v_mov_b32_dpp v171, v71 row_shr:1 row_mask:0xf bank_mask:0xf
	v_pk_fma_f32 v[204:205], v[148:149], v[72:73], v[156:157]
	v_pk_fma_f32 v[112:113], v[132:133], v[64:65], v[140:141]
	v_pk_fma_f32 v[206:207], v[150:151], v[74:75], v[158:159]
	v_pk_fma_f32 v[210:211], v[134:135], v[66:67], v[142:143]
	v_pk_fma_f32 v[204:205], v[152:153], v[76:77], v[204:205]
	v_pk_fma_f32 v[112:113], v[128:129], v[68:69], v[112:113]
	v_pk_fma_f32 v[206:207], v[154:155], v[78:79], v[206:207]
	v_pk_fma_f32 v[210:211], v[130:131], v[70:71], v[210:211]
	v_pk_fma_f32 v[204:205], v[144:145], v[84:85], v[204:205]
	v_pk_fma_f32 v[112:113], v[136:137], v[80:81], v[112:113]
	v_pk_fma_f32 v[206:207], v[146:147], v[86:87], v[206:207]
	v_pk_fma_f32 v[210:211], v[138:139], v[82:83], v[210:211]
	v_pk_mul_f32 v[226:227], v[204:205], v[126:127]
	v_pk_mul_f32 v[228:229], v[206:207], v[126:127]
	v_exp_f32_e32 v226, v226
	v_exp_f32_e32 v227, v227
	v_exp_f32_e32 v228, v228
	v_exp_f32_e32 v229, v229
	s_nop 0
	v_pk_add_f32 v[226:227], v[226:227], 1.0 op_sel_hi:[1,0]
	v_pk_add_f32 v[228:229], v[228:229], 1.0 op_sel_hi:[1,0]
	v_rcp_f32_e32 v226, v226
	v_rcp_f32_e32 v227, v227
	v_rcp_f32_e32 v228, v228
	v_rcp_f32_e32 v229, v229
	s_nop 0
	v_pk_mul_f32 v[204:205], v[204:205], v[226:227]
	v_pk_mul_f32 v[206:207], v[206:207], v[228:229]
	v_pk_mul_f32 v[204:205], v[204:205], v[112:113]
	v_pk_mul_f32 v[206:207], v[206:207], v[210:211]
	v_cvt_pk_bf16_f32 v72, v204, v205
	v_cvt_pk_bf16_f32 v73, v206, v207
	v_pk_fma_f32 v[204:205], v[148:149], v[76:77], v[156:157]
	v_pk_fma_f32 v[112:113], v[132:133], v[68:69], v[140:141]
	v_pk_fma_f32 v[206:207], v[150:151], v[78:79], v[158:159]
	v_pk_fma_f32 v[210:211], v[134:135], v[70:71], v[142:143]
	v_pk_fma_f32 v[204:205], v[152:153], v[84:85], v[204:205]
	v_pk_fma_f32 v[112:113], v[128:129], v[80:81], v[112:113]
	v_pk_fma_f32 v[206:207], v[154:155], v[86:87], v[206:207]
	v_pk_fma_f32 v[210:211], v[130:131], v[82:83], v[210:211]
	v_pk_fma_f32 v[204:205], v[144:145], v[92:93], v[204:205]
	v_pk_fma_f32 v[112:113], v[136:137], v[88:89], v[112:113]
	v_pk_fma_f32 v[206:207], v[146:147], v[94:95], v[206:207]
	v_pk_fma_f32 v[210:211], v[138:139], v[90:91], v[210:211]
	v_pk_mul_f32 v[226:227], v[204:205], v[126:127]
	v_pk_mul_f32 v[228:229], v[206:207], v[126:127]
	v_exp_f32_e32 v226, v226
	v_exp_f32_e32 v227, v227
	v_exp_f32_e32 v228, v228
	v_exp_f32_e32 v229, v229
	s_nop 0
	v_pk_add_f32 v[226:227], v[226:227], 1.0 op_sel_hi:[1,0]
	v_pk_add_f32 v[228:229], v[228:229], 1.0 op_sel_hi:[1,0]
	v_rcp_f32_e32 v226, v226
	v_rcp_f32_e32 v227, v227
	v_rcp_f32_e32 v228, v228
	v_rcp_f32_e32 v229, v229
	s_nop 0
	v_pk_mul_f32 v[204:205], v[204:205], v[226:227]
	v_pk_mul_f32 v[206:207], v[206:207], v[228:229]
	v_pk_mul_f32 v[204:205], v[204:205], v[112:113]
	v_pk_mul_f32 v[206:207], v[206:207], v[210:211]
	v_cvt_pk_bf16_f32 v76, v204, v205
	v_cvt_pk_bf16_f32 v77, v206, v207
	v_pk_fma_f32 v[204:205], v[148:149], v[84:85], v[156:157]
	v_pk_fma_f32 v[112:113], v[132:133], v[80:81], v[140:141]
	v_pk_fma_f32 v[206:207], v[150:151], v[86:87], v[158:159]
	v_pk_fma_f32 v[210:211], v[134:135], v[82:83], v[142:143]
	v_pk_fma_f32 v[204:205], v[152:153], v[92:93], v[204:205]
	v_pk_fma_f32 v[112:113], v[128:129], v[88:89], v[112:113]
	v_pk_fma_f32 v[206:207], v[154:155], v[94:95], v[206:207]
	v_pk_fma_f32 v[210:211], v[130:131], v[90:91], v[210:211]
	v_pk_fma_f32 v[204:205], v[144:145], v[172:173], v[204:205]
	v_pk_fma_f32 v[112:113], v[136:137], v[164:165], v[112:113]
	v_pk_fma_f32 v[206:207], v[146:147], v[174:175], v[206:207]
	v_pk_fma_f32 v[210:211], v[138:139], v[166:167], v[210:211]
	v_pk_mul_f32 v[226:227], v[204:205], v[126:127]
	v_pk_mul_f32 v[228:229], v[206:207], v[126:127]
	v_exp_f32_e32 v226, v226
	v_exp_f32_e32 v227, v227
	v_exp_f32_e32 v228, v228
	v_exp_f32_e32 v229, v229
	s_nop 0
	v_pk_add_f32 v[226:227], v[226:227], 1.0 op_sel_hi:[1,0]
	v_pk_add_f32 v[228:229], v[228:229], 1.0 op_sel_hi:[1,0]
	v_rcp_f32_e32 v226, v226
	v_rcp_f32_e32 v227, v227
	v_rcp_f32_e32 v228, v228
	v_rcp_f32_e32 v229, v229
	s_nop 0
	v_pk_mul_f32 v[204:205], v[204:205], v[226:227]
	v_pk_mul_f32 v[206:207], v[206:207], v[228:229]
	v_pk_mul_f32 v[204:205], v[204:205], v[112:113]
	v_pk_mul_f32 v[206:207], v[206:207], v[210:211]
	v_cvt_pk_bf16_f32 v84, v204, v205
	v_cvt_pk_bf16_f32 v85, v206, v207
	v_pk_fma_f32 v[204:205], v[148:149], v[92:93], v[156:157]
	v_pk_fma_f32 v[112:113], v[132:133], v[88:89], v[140:141]
	v_pk_fma_f32 v[206:207], v[150:151], v[94:95], v[158:159]
	v_pk_fma_f32 v[210:211], v[134:135], v[90:91], v[142:143]
	v_pk_fma_f32 v[204:205], v[152:153], v[172:173], v[204:205]
	v_pk_fma_f32 v[112:113], v[128:129], v[164:165], v[112:113]
	v_pk_fma_f32 v[206:207], v[154:155], v[174:175], v[206:207]
; #define LAS __attribute__((address_space(3)))
;     __device__ __forceinline__ void operator()(const f32x4 (&acc)[2][2][4][2], const pg8::Unit& u, int wr, int wc, int fr, int fq) const {
;     ...
;         for (int n = 0; n < 2; ++n) {
;             const int jg = u.pn * 128 + cc0 + 4 * n;
;             const f32x4 g0w = *(const f32x4*)(cw + jg), g1w = *(const f32x4*)(cw + UPW + jg), g2w = *(const f32x4*)(cw + 2 * UPW + jg), gb = *(const f32x4*)(cb + jg);
;             const f32x4 u0w = *(const f32x4*)(cw + DFF + jg), u1w = *(const f32x4*)(cw + UPW + DFF + jg), u2w = *(const f32x4*)(cw + 2 * UPW + DFF + jg), ub = *(const f32x4*)(cb + DFF + jg);
; #pragma unroll
;             for (int ai = 0; ai < 2; ++ai) {
;                 const int gi = 2 * ai + wr;
;                 f32x4 pg1 = (f32x4){0.f, 0.f, 0.f, 0.f}, pg2 = pg1, pu1 = pg1, pu2 = pg1;
;                 if (gi > 0) {
;                     const LAS float* xp = xb + ((gi - 1) * 2) * 256 + cc0 + 4 * n;
;                     pg1 = *(const LAS f32x4*)(xp + 256); pu1 = *(const LAS f32x4*)(xp + 256 + 128);
;                     pg2 = *(const LAS f32x4*)(xp + (fr & 1) * 256); pu2 = *(const LAS f32x4*)(xp + (fr & 1) * 256 + 128);
;                 }
; #pragma unroll
;                 for (int m = 0; m < 4; ++m) {
;                     float a[4];
; #pragma unroll
;                     for (int e = 0; e < 4; ++e) {
;                         const float gc = acc[ai][0][m][n][e], uc = acc[ai][1][m][n][e];
;                         float og1, og2, ou1, ou2;
;                         if (m == 0) { og1 = pg1[e]; og2 = pg2[e]; ou1 = pu1[e]; ou2 = pu2[e]; }
;                         else { const float gp = acc[ai][0][m - 1][n][e], up = acc[ai][1][m - 1][n][e]; og1 = dpp_ror1(gp); og2 = dpp_ror2(gp); ou1 = dpp_ror1(up); ou2 = dpp_ror2(up); }
;                         const float gm1 = dpp_shr1(og1, gc), gm2 = dpp_shr2(og2, gc), um1 = dpp_shr1(ou1, uc), um2 = dpp_shr2(ou2, uc);
;                         const float yg = g0w[e] * gm2 + g1w[e] * gm1 + g2w[e] * gc + gb[e];
;                         const float yu = u0w[e] * um2 + u1w[e] * um1 + u2w[e] * uc + ub[e];
;                         a[e] = fast_silu(yg) * yu;
;                     }
;                     u32x2 pk; pk.x = cvt_pk_bf16(a[0], a[1]); pk.y = cvt_pk_bf16(a[2], a[3]);
;                     if (n == 0) lo[ai][m] = pk;
;                     else {
	v_pk_fma_f32 v[210:211], v[130:131], v[166:167], v[210:211]
	v_pk_fma_f32 v[204:205], v[144:145], v[176:177], v[204:205]
	v_pk_fma_f32 v[112:113], v[136:137], v[168:169], v[112:113]
	v_pk_fma_f32 v[206:207], v[146:147], v[178:179], v[206:207]
	v_pk_fma_f32 v[210:211], v[138:139], v[170:171], v[210:211]
	v_pk_mul_f32 v[226:227], v[204:205], v[126:127]
	v_pk_mul_f32 v[228:229], v[206:207], v[126:127]
	v_exp_f32_e32 v226, v226
	v_exp_f32_e32 v227, v227
	v_exp_f32_e32 v228, v228
	v_exp_f32_e32 v229, v229
	s_nop 0
	v_pk_add_f32 v[226:227], v[226:227], 1.0 op_sel_hi:[1,0]
	v_pk_add_f32 v[228:229], v[228:229], 1.0 op_sel_hi:[1,0]
	v_rcp_f32_e32 v226, v226
	v_rcp_f32_e32 v227, v227
	v_rcp_f32_e32 v228, v228
	v_rcp_f32_e32 v229, v229
	s_nop 0
	v_pk_mul_f32 v[204:205], v[204:205], v[226:227]
	v_pk_mul_f32 v[206:207], v[206:207], v[228:229]
	v_pk_mul_f32 v[204:205], v[204:205], v[112:113]
	v_pk_mul_f32 v[206:207], v[206:207], v[210:211]
	v_cvt_pk_bf16_f32 v92, v204, v205
	v_cvt_pk_bf16_f32 v93, v206, v207
	global_load_dwordx4 v[144:147], v244, s[84:85] offset:16
	global_load_dwordx4 v[152:155], v244, s[30:31] offset:16
	global_load_dwordx4 v[148:151], v244, s[34:35] offset:16
	global_load_dwordx4 v[156:159], v244, s[86:87] offset:16
	global_load_dwordx4 v[136:139], v244, s[36:37] offset:16
	global_load_dwordx4 v[128:131], v244, s[38:39] offset:16
	global_load_dwordx4 v[132:135], v244, s[40:41] offset:16
	global_load_dwordx4 v[140:143], v244, s[42:43] offset:16
	v_mov_b32_e32 v172, 0
	v_mov_b32_e32 v173, 0
	v_mov_b32_e32 v174, 0
	v_mov_b32_e32 v175, 0
	v_mov_b32_e32 v164, 0
	v_mov_b32_e32 v165, 0
	v_mov_b32_e32 v166, 0
	v_mov_b32_e32 v167, 0
	v_mov_b32_e32 v176, 0
	v_mov_b32_e32 v177, 0
	v_mov_b32_e32 v178, 0
	v_mov_b32_e32 v179, 0
	v_mov_b32_e32 v168, 0
	v_mov_b32_e32 v169, 0
	v_mov_b32_e32 v170, 0
	v_mov_b32_e32 v171, 0
	s_andn2_b64 vcc, exec, s[24:25]
	s_cbranch_vccnz .Lupc2_nocarry10
	ds_read_b128 v[172:175], v215 offset:1040
	ds_read_b128 v[164:167], v215 offset:1552
	ds_read_b128 v[176:179], v215 offset:16
	ds_read_b128 v[168:171], v215 offset:528
.Lupc2_nocarry10:
	s_waitcnt vmcnt(0) lgkmcnt(0)
	v_mov_b32_dpp v172, v40 row_shr:1 row_mask:0xf bank_mask:0xf
	v_mov_b32_dpp v176, v44 row_shr:1 row_mask:0xf bank_mask:0xf
	v_mov_b32_dpp v164, v32 row_shr:1 row_mask:0xf bank_mask:0xf
	v_mov_b32_dpp v168, v36 row_shr:1 row_mask:0xf bank_mask:0xf
	v_mov_b32_dpp v173, v41 row_shr:1 row_mask:0xf bank_mask:0xf
	v_mov_b32_dpp v177, v45 row_shr:1 row_mask:0xf bank_mask:0xf
	v_mov_b32_dpp v165, v33 row_shr:1 row_mask:0xf bank_mask:0xf
	v_mov_b32_dpp v169, v37 row_shr:1 row_mask:0xf bank_mask:0xf
	v_mov_b32_dpp v174, v42 row_shr:1 row_mask:0xf bank_mask:0xf
	v_mov_b32_dpp v178, v46 row_shr:1 row_mask:0xf bank_mask:0xf
	v_mov_b32_dpp v166, v34 row_shr:1 row_mask:0xf bank_mask:0xf
	v_mov_b32_dpp v170, v38 row_shr:1 row_mask:0xf bank_mask:0xf
	v_mov_b32_dpp v175, v43 row_shr:1 row_mask:0xf bank_mask:0xf
	v_mov_b32_dpp v179, v47 row_shr:1 row_mask:0xf bank_mask:0xf
	v_mov_b32_dpp v167, v35 row_shr:1 row_mask:0xf bank_mask:0xf
	v_mov_b32_dpp v171, v39 row_shr:1 row_mask:0xf bank_mask:0xf
	v_pk_fma_f32 v[204:205], v[148:149], v[40:41], v[156:157]
	v_pk_fma_f32 v[112:113], v[132:133], v[32:33], v[140:141]
	v_pk_fma_f32 v[206:207], v[150:151], v[42:43], v[158:159]
	v_pk_fma_f32 v[210:211], v[134:135], v[34:35], v[142:143]
	v_pk_fma_f32 v[204:205], v[152:153], v[44:45], v[204:205]
	v_pk_fma_f32 v[112:113], v[128:129], v[36:37], v[112:113]
	v_pk_fma_f32 v[206:207], v[154:155], v[46:47], v[206:207]
	v_pk_fma_f32 v[210:211], v[130:131], v[38:39], v[210:211]
	v_pk_fma_f32 v[204:205], v[144:145], v[52:53], v[204:205]
	v_pk_fma_f32 v[112:113], v[136:137], v[48:49], v[112:113]
	v_pk_fma_f32 v[206:207], v[146:147], v[54:55], v[206:207]
	v_pk_fma_f32 v[210:211], v[138:139], v[50:51], v[210:211]
	v_pk_mul_f32 v[226:227], v[204:205], v[126:127]
	v_pk_mul_f32 v[228:229], v[206:207], v[126:127]
	v_exp_f32_e32 v226, v226
	v_exp_f32_e32 v227, v227
	v_exp_f32_e32 v228, v228
	v_exp_f32_e32 v229, v229
	s_nop 0
	v_pk_add_f32 v[226:227], v[226:227], 1.0 op_sel_hi:[1,0]
	v_pk_add_f32 v[228:229], v[228:229], 1.0 op_sel_hi:[1,0]
	v_rcp_f32_e32 v226, v226
	v_rcp_f32_e32 v227, v227
	v_rcp_f32_e32 v228, v228
	v_rcp_f32_e32 v229, v229
	s_nop 0
	v_pk_mul_f32 v[204:205], v[204:205], v[226:227]
	v_pk_mul_f32 v[206:207], v[206:207], v[228:229]
	v_pk_mul_f32 v[204:205], v[204:205], v[112:113]
	v_pk_mul_f32 v[206:207], v[206:207], v[210:211]
	v_cvt_pk_bf16_f32 v106, v204, v205
	v_cvt_pk_bf16_f32 v107, v206, v207
	v_add_u32_e32 v242, 0x8400, v243
	global_store_dwordx4 v242, v[104:107], s[14:15] nt
	v_pk_fma_f32 v[204:205], v[148:149], v[44:45], v[156:157]
	v_pk_fma_f32 v[112:113], v[132:133], v[36:37], v[140:141]
	v_pk_fma_f32 v[206:207], v[150:151], v[46:47], v[158:159]
	v_pk_fma_f32 v[210:211], v[134:135], v[38:39], v[142:143]
	v_pk_fma_f32 v[204:205], v[152:153], v[52:53], v[204:205]
	v_pk_fma_f32 v[112:113], v[128:129], v[48:49], v[112:113]
	v_pk_fma_f32 v[206:207], v[154:155], v[54:55], v[206:207]
	v_pk_fma_f32 v[210:211], v[130:131], v[50:51], v[210:211]
	v_pk_fma_f32 v[204:205], v[144:145], v[60:61], v[204:205]
	v_pk_fma_f32 v[112:113], v[136:137], v[56:57], v[112:113]
	v_pk_fma_f32 v[206:207], v[146:147], v[62:63], v[206:207]
	v_pk_fma_f32 v[210:211], v[138:139], v[58:59], v[210:211]
	v_pk_mul_f32 v[226:227], v[204:205], v[126:127]
	v_pk_mul_f32 v[228:229], v[206:207], v[126:127]
	v_exp_f32_e32 v226, v226
	v_exp_f32_e32 v227, v227
	v_exp_f32_e32 v228, v228
	v_exp_f32_e32 v229, v229
	s_nop 0
	v_pk_add_f32 v[226:227], v[226:227], 1.0 op_sel_hi:[1,0]
	v_pk_add_f32 v[228:229], v[228:229], 1.0 op_sel_hi:[1,0]
; __device__ __forceinline__ unsigned cvt_pk_bf16(float lo, float hi) { unsigned r; asm volatile("v_cvt_pk_bf16_f32 %0, %1, %2" : "=v"(r) : "v"(lo), "v"(hi)); return r; }
; __device__ __forceinline__ float fast_silu(float x) { return x * fast_sigmoid(x); }
; __device__ __forceinline__ float dpp_shr1(float old, float src) { return __int_as_float(__builtin_amdgcn_update_dpp(__float_as_int(old), __float_as_int(src), 0x111, 0xf, 0xf, false)); }
; __device__ __forceinline__ float dpp_shr2(float old, float src) { return __int_as_float(__builtin_amdgcn_update_dpp(__float_as_int(old), __float_as_int(src), 0x112, 0xf, 0xf, false)); }
; __device__ __forceinline__ float dpp_ror1(float src) { return __int_as_float(__builtin_amdgcn_mov_dpp(__float_as_int(src), 0x121, 0xf, 0xf, true)); }
;     __device__ __forceinline__ void operator()(const f32x4 (&acc)[2][2][4][2], const pg8::Unit& u, int wr, int wc, int fr, int fq) const {
;     ...
; #pragma unroll
;                 for (int m = 0; m < 4; ++m) {
;                     float a[4];
; #pragma unroll
;                     for (int e = 0; e < 4; ++e) {
;                         const float gc = acc[ai][0][m][n][e], uc = acc[ai][1][m][n][e];
;                         float og1, og2, ou1, ou2;
;                         if (m == 0) { og1 = pg1[e]; og2 = pg2[e]; ou1 = pu1[e]; ou2 = pu2[e]; }
;                         else { const float gp = acc[ai][0][m - 1][n][e], up = acc[ai][1][m - 1][n][e]; og1 = dpp_ror1(gp); og2 = dpp_ror2(gp); ou1 = dpp_ror1(up); ou2 = dpp_ror2(up); }
;                         const float gm1 = dpp_shr1(og1, gc), gm2 = dpp_shr2(og2, gc), um1 = dpp_shr1(ou1, uc), um2 = dpp_shr2(ou2, uc);
;                         const float yg = g0w[e] * gm2 + g1w[e] * gm1 + g2w[e] * gc + gb[e];
;                         const float yu = u0w[e] * um2 + u1w[e] * um1 + u2w[e] * uc + ub[e];
;                         a[e] = fast_silu(yg) * yu;
;                     }
;                     u32x2 pk; pk.x = cvt_pk_bf16(a[0], a[1]); pk.y = cvt_pk_bf16(a[2], a[3]);
;                     if (n == 0) lo[ai][m] = pk;
;                     else {
;                         const bool skip = (gi == 0) && (m == 0) && (fr < 2);
;                         if (!skip) __builtin_nontemporal_store((u32x4){lo[ai][m].x, lo[ai][m].y, pk.x, pk.y}, (u32x4*)(ACT + (size_t)(row0 + ai * 128 + m * 16) * DFF + u.pn * 128 + cc0));
;                     }
	v_rcp_f32_e32 v226, v226
	v_rcp_f32_e32 v227, v227
	v_rcp_f32_e32 v228, v228
	v_rcp_f32_e32 v229, v229
	s_nop 0
	v_pk_mul_f32 v[204:205], v[204:205], v[226:227]
	v_pk_mul_f32 v[206:207], v[206:207], v[228:229]
	v_pk_mul_f32 v[204:205], v[204:205], v[112:113]
	v_pk_mul_f32 v[206:207], v[206:207], v[210:211]
	v_cvt_pk_bf16_f32 v110, v204, v205
	v_cvt_pk_bf16_f32 v111, v206, v207
	v_add_u32_e32 v242, 0x5800, v243
	global_store_dwordx4 v242, v[108:111], s[14:15] nt
	v_pk_fma_f32 v[204:205], v[148:149], v[52:53], v[156:157]
	v_pk_fma_f32 v[112:113], v[132:133], v[48:49], v[140:141]
	v_pk_fma_f32 v[206:207], v[150:151], v[54:55], v[158:159]
	v_pk_fma_f32 v[210:211], v[134:135], v[50:51], v[142:143]
	v_pk_fma_f32 v[204:205], v[152:153], v[60:61], v[204:205]
	v_pk_fma_f32 v[112:113], v[128:129], v[56:57], v[112:113]
	v_pk_fma_f32 v[206:207], v[154:155], v[62:63], v[206:207]
	v_pk_fma_f32 v[210:211], v[130:131], v[58:59], v[210:211]
	v_pk_fma_f32 v[204:205], v[144:145], v[172:173], v[204:205]
	v_pk_fma_f32 v[112:113], v[136:137], v[164:165], v[112:113]
	v_pk_fma_f32 v[206:207], v[146:147], v[174:175], v[206:207]
	v_pk_fma_f32 v[210:211], v[138:139], v[166:167], v[210:211]
	v_pk_mul_f32 v[226:227], v[204:205], v[126:127]
	v_pk_mul_f32 v[228:229], v[206:207], v[126:127]
	v_exp_f32_e32 v226, v226
	v_exp_f32_e32 v227, v227
	v_exp_f32_e32 v228, v228
	v_exp_f32_e32 v229, v229
	s_nop 0
	v_pk_add_f32 v[226:227], v[226:227], 1.0 op_sel_hi:[1,0]
	v_pk_add_f32 v[228:229], v[228:229], 1.0 op_sel_hi:[1,0]
	v_rcp_f32_e32 v226, v226
	v_rcp_f32_e32 v227, v227
	v_rcp_f32_e32 v228, v228
	v_rcp_f32_e32 v229, v229
	s_nop 0
	v_pk_mul_f32 v[204:205], v[204:205], v[226:227]
	v_pk_mul_f32 v[206:207], v[206:207], v[228:229]
	v_pk_mul_f32 v[204:205], v[204:205], v[112:113]
	v_pk_mul_f32 v[206:207], v[206:207], v[210:211]
	v_cvt_pk_bf16_f32 v124, v204, v205
	v_cvt_pk_bf16_f32 v125, v206, v207
	v_add_u32_e32 v242, 0x2c00, v243
	s_and_saveexec_b64 s[8:9], s[78:79]
	global_store_dwordx4 v242, v[122:125], s[14:15] nt
	s_or_b64 exec, exec, s[8:9]
	v_pk_fma_f32 v[204:205], v[148:149], v[60:61], v[156:157]
	v_pk_fma_f32 v[112:113], v[132:133], v[56:57], v[140:141]
	v_pk_fma_f32 v[206:207], v[150:151], v[62:63], v[158:159]
	v_pk_fma_f32 v[210:211], v[134:135], v[58:59], v[142:143]
	v_pk_fma_f32 v[204:205], v[152:153], v[172:173], v[204:205]
	v_pk_fma_f32 v[112:113], v[128:129], v[164:165], v[112:113]
	v_pk_fma_f32 v[206:207], v[154:155], v[174:175], v[206:207]
	v_pk_fma_f32 v[210:211], v[130:131], v[166:167], v[210:211]
	v_pk_fma_f32 v[204:205], v[144:145], v[176:177], v[204:205]
	v_pk_fma_f32 v[112:113], v[136:137], v[168:169], v[112:113]
	v_pk_fma_f32 v[206:207], v[146:147], v[178:179], v[206:207]
	v_pk_fma_f32 v[210:211], v[138:139], v[170:171], v[210:211]
	v_pk_mul_f32 v[226:227], v[204:205], v[126:127]
	v_pk_mul_f32 v[228:229], v[206:207], v[126:127]
	v_exp_f32_e32 v226, v226
	v_exp_f32_e32 v227, v227
	v_exp_f32_e32 v228, v228
	v_exp_f32_e32 v229, v229
	s_nop 0
	v_pk_add_f32 v[226:227], v[226:227], 1.0 op_sel_hi:[1,0]
	v_pk_add_f32 v[228:229], v[228:229], 1.0 op_sel_hi:[1,0]
	v_rcp_f32_e32 v226, v226
	v_rcp_f32_e32 v227, v227
	v_rcp_f32_e32 v228, v228
	v_rcp_f32_e32 v229, v229
	s_nop 0
	v_pk_mul_f32 v[204:205], v[204:205], v[226:227]
	v_pk_mul_f32 v[206:207], v[206:207], v[228:229]
	v_pk_mul_f32 v[204:205], v[204:205], v[112:113]
	v_pk_mul_f32 v[206:207], v[206:207], v[210:211]
	v_cvt_pk_bf16_f32 v162, v204, v205
	v_cvt_pk_bf16_f32 v163, v206, v207
	v_mov_b32_e32 v242, v243
	s_and_saveexec_b64 s[8:9], s[78:79]
	global_store_dwordx4 v242, v[160:163], s[14:15] nt
	s_or_b64 exec, exec, s[8:9]
	ds_read_b128 v[172:175], v215 offset:5136
	ds_read_b128 v[164:167], v215 offset:5648
	ds_read_b128 v[176:179], v215 offset:4112
	ds_read_b128 v[168:171], v215 offset:4624
	s_waitcnt lgkmcnt(0)
	v_mov_b32_dpp v172, v8 row_shr:1 row_mask:0xf bank_mask:0xf
	v_mov_b32_dpp v176, v12 row_shr:1 row_mask:0xf bank_mask:0xf
	v_mov_b32_dpp v164, v0 row_shr:1 row_mask:0xf bank_mask:0xf
	v_mov_b32_dpp v168, v4 row_shr:1 row_mask:0xf bank_mask:0xf
	v_mov_b32_dpp v173, v9 row_shr:1 row_mask:0xf bank_mask:0xf
	v_mov_b32_dpp v177, v13 row_shr:1 row_mask:0xf bank_mask:0xf
	v_mov_b32_dpp v165, v1 row_shr:1 row_mask:0xf bank_mask:0xf
	v_mov_b32_dpp v169, v5 row_shr:1 row_mask:0xf bank_mask:0xf
	v_mov_b32_dpp v174, v10 row_shr:1 row_mask:0xf bank_mask:0xf
	v_mov_b32_dpp v178, v14 row_shr:1 row_mask:0xf bank_mask:0xf
	v_mov_b32_dpp v166, v2 row_shr:1 row_mask:0xf bank_mask:0xf
	v_mov_b32_dpp v170, v6 row_shr:1 row_mask:0xf bank_mask:0xf
	v_mov_b32_dpp v175, v11 row_shr:1 row_mask:0xf bank_mask:0xf
	v_mov_b32_dpp v179, v15 row_shr:1 row_mask:0xf bank_mask:0xf
	v_mov_b32_dpp v167, v3 row_shr:1 row_mask:0xf bank_mask:0xf
	v_mov_b32_dpp v171, v7 row_shr:1 row_mask:0xf bank_mask:0xf
	v_pk_fma_f32 v[204:205], v[148:149], v[8:9], v[156:157]
	v_pk_fma_f32 v[112:113], v[132:133], v[0:1], v[140:141]
	v_pk_fma_f32 v[206:207], v[150:151], v[10:11], v[158:159]
	v_pk_fma_f32 v[210:211], v[134:135], v[2:3], v[142:143]
	v_pk_fma_f32 v[204:205], v[152:153], v[12:13], v[204:205]
	v_pk_fma_f32 v[112:113], v[128:129], v[4:5], v[112:113]
	v_pk_fma_f32 v[206:207], v[154:155], v[14:15], v[206:207]
	v_pk_fma_f32 v[210:211], v[130:131], v[6:7], v[210:211]
	v_pk_fma_f32 v[204:205], v[144:145], v[20:21], v[204:205]
	v_pk_fma_f32 v[112:113], v[136:137], v[16:17], v[112:113]
	v_pk_fma_f32 v[206:207], v[146:147], v[22:23], v[206:207]
	v_pk_fma_f32 v[210:211], v[138:139], v[18:19], v[210:211]
; __device__ __forceinline__ unsigned cvt_pk_bf16(float lo, float hi) { unsigned r; asm volatile("v_cvt_pk_bf16_f32 %0, %1, %2" : "=v"(r) : "v"(lo), "v"(hi)); return r; }
; __device__ __forceinline__ float fast_silu(float x) { return x * fast_sigmoid(x); }
; __device__ __forceinline__ float dpp_shr1(float old, float src) { return __int_as_float(__builtin_amdgcn_update_dpp(__float_as_int(old), __float_as_int(src), 0x111, 0xf, 0xf, false)); }
; __device__ __forceinline__ float dpp_shr2(float old, float src) { return __int_as_float(__builtin_amdgcn_update_dpp(__float_as_int(old), __float_as_int(src), 0x112, 0xf, 0xf, false)); }
; __device__ __forceinline__ float dpp_ror1(float src) { return __int_as_float(__builtin_amdgcn_mov_dpp(__float_as_int(src), 0x121, 0xf, 0xf, true)); }
;     __device__ __forceinline__ void operator()(const f32x4 (&acc)[2][2][4][2], const pg8::Unit& u, int wr, int wc, int fr, int fq) const {
;     ...
; #pragma unroll
;                 for (int m = 0; m < 4; ++m) {
;                     float a[4];
; #pragma unroll
;                     for (int e = 0; e < 4; ++e) {
;                         const float gc = acc[ai][0][m][n][e], uc = acc[ai][1][m][n][e];
;                         float og1, og2, ou1, ou2;
;                         if (m == 0) { og1 = pg1[e]; og2 = pg2[e]; ou1 = pu1[e]; ou2 = pu2[e]; }
;                         else { const float gp = acc[ai][0][m - 1][n][e], up = acc[ai][1][m - 1][n][e]; og1 = dpp_ror1(gp); og2 = dpp_ror2(gp); ou1 = dpp_ror1(up); ou2 = dpp_ror2(up); }
;                         const float gm1 = dpp_shr1(og1, gc), gm2 = dpp_shr2(og2, gc), um1 = dpp_shr1(ou1, uc), um2 = dpp_shr2(ou2, uc);
;                         const float yg = g0w[e] * gm2 + g1w[e] * gm1 + g2w[e] * gc + gb[e];
;                         const float yu = u0w[e] * um2 + u1w[e] * um1 + u2w[e] * uc + ub[e];
;                         a[e] = fast_silu(yg) * yu;
;                     }
;                     u32x2 pk; pk.x = cvt_pk_bf16(a[0], a[1]); pk.y = cvt_pk_bf16(a[2], a[3]);
;                     if (n == 0) lo[ai][m] = pk;
;                     else {
;                         const bool skip = (gi == 0) && (m == 0) && (fr < 2);
;                         if (!skip) __builtin_nontemporal_store((u32x4){lo[ai][m].x, lo[ai][m].y, pk.x, pk.y}, (u32x4*)(ACT + (size_t)(row0 + ai * 128 + m * 16) * DFF + u.pn * 128 + cc0));
;                     }
	v_pk_mul_f32 v[226:227], v[204:205], v[126:127]
	v_pk_mul_f32 v[228:229], v[206:207], v[126:127]
	v_exp_f32_e32 v226, v226
	v_exp_f32_e32 v227, v227
	v_exp_f32_e32 v228, v228
	v_exp_f32_e32 v229, v229
	s_nop 0
	v_pk_add_f32 v[226:227], v[226:227], 1.0 op_sel_hi:[1,0]
	v_pk_add_f32 v[228:229], v[228:229], 1.0 op_sel_hi:[1,0]
	v_rcp_f32_e32 v226, v226
	v_rcp_f32_e32 v227, v227
	v_rcp_f32_e32 v228, v228
	v_rcp_f32_e32 v229, v229
	s_nop 0
	v_pk_mul_f32 v[204:205], v[204:205], v[226:227]
	v_pk_mul_f32 v[206:207], v[206:207], v[228:229]
	v_pk_mul_f32 v[204:205], v[204:205], v[112:113]
	v_pk_mul_f32 v[206:207], v[206:207], v[210:211]
	v_cvt_pk_bf16_f32 v74, v204, v205
	v_cvt_pk_bf16_f32 v75, v206, v207
	v_add_u32_e32 v242, 0x168400, v243
	global_store_dwordx4 v242, v[72:75], s[14:15] nt
	v_pk_fma_f32 v[204:205], v[148:149], v[12:13], v[156:157]
	v_pk_fma_f32 v[112:113], v[132:133], v[4:5], v[140:141]
	v_pk_fma_f32 v[206:207], v[150:151], v[14:15], v[158:159]
	v_pk_fma_f32 v[210:211], v[134:135], v[6:7], v[142:143]
	v_pk_fma_f32 v[204:205], v[152:153], v[20:21], v[204:205]
	v_pk_fma_f32 v[112:113], v[128:129], v[16:17], v[112:113]
	v_pk_fma_f32 v[206:207], v[154:155], v[22:23], v[206:207]
	v_pk_fma_f32 v[210:211], v[130:131], v[18:19], v[210:211]
	v_pk_fma_f32 v[204:205], v[144:145], v[28:29], v[204:205]
	v_pk_fma_f32 v[112:113], v[136:137], v[24:25], v[112:113]
	v_pk_fma_f32 v[206:207], v[146:147], v[30:31], v[206:207]
	v_pk_fma_f32 v[210:211], v[138:139], v[26:27], v[210:211]
	v_pk_mul_f32 v[226:227], v[204:205], v[126:127]
	v_pk_mul_f32 v[228:229], v[206:207], v[126:127]
	v_exp_f32_e32 v226, v226
	v_exp_f32_e32 v227, v227
	v_exp_f32_e32 v228, v228
	v_exp_f32_e32 v229, v229
	s_nop 0
	v_pk_add_f32 v[226:227], v[226:227], 1.0 op_sel_hi:[1,0]
	v_pk_add_f32 v[228:229], v[228:229], 1.0 op_sel_hi:[1,0]
	v_rcp_f32_e32 v226, v226
	v_rcp_f32_e32 v227, v227
	v_rcp_f32_e32 v228, v228
	v_rcp_f32_e32 v229, v229
	s_nop 0
	v_pk_mul_f32 v[204:205], v[204:205], v[226:227]
	v_pk_mul_f32 v[206:207], v[206:207], v[228:229]
	v_pk_mul_f32 v[204:205], v[204:205], v[112:113]
	v_pk_mul_f32 v[206:207], v[206:207], v[210:211]
	v_cvt_pk_bf16_f32 v78, v204, v205
	v_cvt_pk_bf16_f32 v79, v206, v207
	v_add_u32_e32 v242, 0x165800, v243
	global_store_dwordx4 v242, v[76:79], s[14:15] nt
	v_pk_fma_f32 v[204:205], v[148:149], v[20:21], v[156:157]
	v_pk_fma_f32 v[112:113], v[132:133], v[16:17], v[140:141]
	v_pk_fma_f32 v[206:207], v[150:151], v[22:23], v[158:159]
	v_pk_fma_f32 v[210:211], v[134:135], v[18:19], v[142:143]
	v_pk_fma_f32 v[204:205], v[152:153], v[28:29], v[204:205]
	v_pk_fma_f32 v[112:113], v[128:129], v[24:25], v[112:113]
	v_pk_fma_f32 v[206:207], v[154:155], v[30:31], v[206:207]
	v_pk_fma_f32 v[210:211], v[130:131], v[26:27], v[210:211]
	v_pk_fma_f32 v[204:205], v[144:145], v[172:173], v[204:205]
	v_pk_fma_f32 v[112:113], v[136:137], v[164:165], v[112:113]
	v_pk_fma_f32 v[206:207], v[146:147], v[174:175], v[206:207]
	v_pk_fma_f32 v[210:211], v[138:139], v[166:167], v[210:211]
	v_pk_mul_f32 v[226:227], v[204:205], v[126:127]
	v_pk_mul_f32 v[228:229], v[206:207], v[126:127]
	v_exp_f32_e32 v226, v226
	v_exp_f32_e32 v227, v227
	v_exp_f32_e32 v228, v228
	v_exp_f32_e32 v229, v229
	s_nop 0
	v_pk_add_f32 v[226:227], v[226:227], 1.0 op_sel_hi:[1,0]
	v_pk_add_f32 v[228:229], v[228:229], 1.0 op_sel_hi:[1,0]
	v_rcp_f32_e32 v226, v226
	v_rcp_f32_e32 v227, v227
	v_rcp_f32_e32 v228, v228
	v_rcp_f32_e32 v229, v229
	s_nop 0
	v_pk_mul_f32 v[204:205], v[204:205], v[226:227]
	v_pk_mul_f32 v[206:207], v[206:207], v[228:229]
	v_pk_mul_f32 v[204:205], v[204:205], v[112:113]
	v_pk_mul_f32 v[206:207], v[206:207], v[210:211]
	v_cvt_pk_bf16_f32 v86, v204, v205
	v_cvt_pk_bf16_f32 v87, v206, v207
	v_add_u32_e32 v242, 0x162c00, v243
	global_store_dwordx4 v242, v[84:87], s[14:15] nt
	v_pk_fma_f32 v[204:205], v[148:149], v[28:29], v[156:157]
	v_pk_fma_f32 v[112:113], v[132:133], v[24:25], v[140:141]
	v_pk_fma_f32 v[206:207], v[150:151], v[30:31], v[158:159]
	v_pk_fma_f32 v[210:211], v[134:135], v[26:27], v[142:143]
	v_pk_fma_f32 v[204:205], v[152:153], v[172:173], v[204:205]
	v_pk_fma_f32 v[112:113], v[128:129], v[164:165], v[112:113]
	v_pk_fma_f32 v[206:207], v[154:155], v[174:175], v[206:207]
	v_pk_fma_f32 v[210:211], v[130:131], v[166:167], v[210:211]
	v_pk_fma_f32 v[204:205], v[144:145], v[176:177], v[204:205]
	v_pk_fma_f32 v[112:113], v[136:137], v[168:169], v[112:113]
	v_pk_fma_f32 v[206:207], v[146:147], v[178:179], v[206:207]
	v_pk_fma_f32 v[210:211], v[138:139], v[170:171], v[210:211]
	v_pk_mul_f32 v[226:227], v[204:205], v[126:127]
	v_pk_mul_f32 v[228:229], v[206:207], v[126:127]
	v_exp_f32_e32 v226, v226
	v_exp_f32_e32 v227, v227
	v_exp_f32_e32 v228, v228
	v_exp_f32_e32 v229, v229
	s_nop 0
	v_pk_add_f32 v[226:227], v[226:227], 1.0 op_sel_hi:[1,0]
	v_pk_add_f32 v[228:229], v[228:229], 1.0 op_sel_hi:[1,0]
	v_rcp_f32_e32 v226, v226
	v_rcp_f32_e32 v227, v227
	v_rcp_f32_e32 v228, v228
	v_rcp_f32_e32 v229, v229
	s_nop 0
	v_pk_mul_f32 v[204:205], v[204:205], v[226:227]
	v_pk_mul_f32 v[206:207], v[206:207], v[228:229]
	v_pk_mul_f32 v[204:205], v[204:205], v[112:113]
	v_pk_mul_f32 v[206:207], v[206:207], v[210:211]
	v_cvt_pk_bf16_f32 v94, v204, v205
	v_cvt_pk_bf16_f32 v95, v206, v207
	v_add_u32_e32 v242, 0x160000, v243
	global_store_dwordx4 v242, v[92:95], s[14:15] nt
	s_andn2_b64 vcc, exec, s[4:5]
	s_mov_b64 s[4:5], -1
	s_cbranch_vccnz .LBB0_924
	s_and_b64 vcc, exec, s[6:7]
	s_cbranch_vccnz .LBB0_923
	s_barrier
	s_branch .LBB0_923
